# v20 with the two s_nop pads in the softmax segment replaced by independent bf16 conversions (fewer issue slots)
# baseline (speedup 1.0000x reference)
; #define A128_SBAR() __builtin_amdgcn_sched_barrier(0)
; #define A128_PK4(P, BASE, OUT) do { u32x4 w = {cvt_pk_bf16(P[BASE + 0], P[BASE + 1]), cvt_pk_bf16(P[BASE + 2], P[BASE + 3]), cvt_pk_bf16(P[BASE + 4], P[BASE + 5]), cvt_pk_bf16(P[BASE + 6], P[BASE + 7])}; \
;     OUT = __builtin_bit_cast(bf16x8, w); } while (0)
; #define A128_SWAIT() asm volatile("s_waitcnt vmcnt(3)" ::: "memory")
; __device__ __forceinline__ void finishSM(f32x16& p0, f32x16& p1, float alpha, float& l_reg, bf16x8& pa0, bf16x8& pa1, bf16x8& pa2, bf16x8& pa3) {
; #pragma unroll
;   for (int r = 0; r < 16; ++r) p1[r] = __builtin_amdgcn_exp2f(p1[r]);
;   typedef float f32x8_ __attribute__((ext_vector_type(8))); typedef float f32x2_ __attribute__((ext_vector_type(2)));
;   const f32x16 s16_ = p0 + p1; const f32x8_ s8_ = s16_.lo + s16_.hi; const f32x4 s4_ = s8_.lo + s8_.hi; const f32x2_ s2_ = s4_.lo + s4_.hi;
;   float ps = s2_.x + s2_.y;
;   { auto rr = __builtin_amdgcn_permlane32_swap(__float_as_uint(ps), __float_as_uint(ps), false, false); ps = __uint_as_float(rr[0]) + __uint_as_float(rr[1]); }
;   l_reg = l_reg * alpha + ps;
;     ...
;   A128_PK4(p0, 0, pa0); A128_PK4(p0, 8, pa1); A128_PK4(p1, 0, pa2); A128_PK4(p1, 8, pa3);
;     ...
; }
; __device__ __forceinline__ void unit(const bf16* __restrict__ Qb0, const bf16* __restrict__ Kh0, const bf16* __restrict__ Vh, bf16_t* Ob, int seq, char* lds, const int tid_in, const float lam, const float onem, const float* __restrict__ subw, const float* __restrict__ kmb  ) {
;     ...
;   for (int j = 1; j + 1 < NT; j += 2) {
;     A128_SBAR(); qkt(pB0, pB1, K_lds + SHM_K, qr, r32, hi);
;     finishSM(pA0, pA1, alA, l_reg, pa0, pa1, pa2, pa3); A128_SBAR();
;     A128_SLOAD(1, (j + 2) * KVBLK); A128_SBAR();
;     pv_d0(o, vb0, pa0, pa1, pa2, pa3); partialSM(pB0, pB1, m_reg, mnB, alB, nomax);
;     __syncthreads(); A128_SWAIT(); A128_SWRITE(0, 0);
;     if (!nomax) A128_RESC(alB); __syncthreads();
;     A128_SBAR(); qkt(pA0, pA1, K_lds, qr, r32, hi);
;     finishSM(pB0, pB1, alB, l_reg, pa0, pa1, pa2, pa3); A128_SBAR();
;     if (j + 3 < NT) A128_SLOAD(0, (j + 3) * KVBLK); A128_SBAR();
;     pv_d0(o, vb0 + (int)SHM_V, pa0, pa1, pa2, pa3); partialSM(pA0, pA1, m_reg, mnA, alA, nomax);
;     __syncthreads(); A128_SWAIT(); A128_SWRITE(1, 1);
;     if (!nomax) A128_RESC(alA); __syncthreads();
;   }
.Lfa_loop:
	s_barrier
	s_setprio 1
	ds_read_b128 v[2:5], v204 offset:40960
	ds_read_b128 v[6:9], v204 offset:45056
	ds_read_b128 v[10:13], v205 offset:40960
	ds_read_b128 v[162:165], v205 offset:45056
	s_waitcnt lgkmcnt(2)
	v_mfma_f32_32x32x16_bf16 v[112:127], v[2:5], v[140:143], 0
	ds_read_b128 v[168:171], v192 offset:40960
	ds_read_b128 v[172:175], v192 offset:45056
	v_mfma_f32_32x32x16_bf16 v[96:111], v[6:9], v[140:143], 0
	ds_read_b128 v[176:179], v193 offset:40960
	ds_read_b128 v[194:197], v193 offset:45056
	s_waitcnt lgkmcnt(4)
	v_mfma_f32_32x32x16_bf16 v[112:127], v[10:13], v[136:139], v[112:127]
	ds_read_b64_tr_b16 v[210:211], v190 offset:0x0
	ds_read_b64_tr_b16 v[212:213], v190 offset:0x800
	ds_read_b64_tr_b16 v[214:215], v190 offset:0x1000
	v_mfma_f32_32x32x16_bf16 v[96:111], v[162:165], v[136:139], v[96:111]
	ds_read_b64_tr_b16 v[216:217], v190 offset:0x1800
	ds_read_b64_tr_b16 v[244:245], v190 offset:0x2000
	ds_read_b64_tr_b16 v[246:247], v190 offset:0x2800
	s_waitcnt lgkmcnt(8)
	v_mfma_f32_32x32x16_bf16 v[112:127], v[168:171], v[132:135], v[112:127]
	ds_read_b64_tr_b16 v[248:249], v190 offset:0x3000
	ds_read_b64_tr_b16 v[250:251], v190 offset:0x3800
	v_mfma_f32_32x32x16_bf16 v[96:111], v[172:175], v[132:135], v[96:111]
	ds_read_b64_tr_b16 v[2:3], v190 offset:0x200
	ds_read_b64_tr_b16 v[4:5], v190 offset:0xa00
	ds_read_b64_tr_b16 v[6:7], v190 offset:0x1200
	s_waitcnt lgkmcnt(11)
	v_mfma_f32_32x32x16_bf16 v[112:127], v[176:179], v[128:131], v[112:127]
	ds_read_b64_tr_b16 v[8:9], v190 offset:0x1a00
	ds_read_b64_tr_b16 v[10:11], v190 offset:0x2200
	ds_read_b64_tr_b16 v[12:13], v190 offset:0x2a00
	v_mfma_f32_32x32x16_bf16 v[96:111], v[194:197], v[128:131], v[96:111]
	ds_read_b64_tr_b16 v[162:163], v190 offset:0x3200
	ds_read_b64_tr_b16 v[164:165], v190 offset:0x3a00
	s_waitcnt vmcnt(3)
	ds_write_b128 v203, v[144:147] offset:32768
	ds_write_b128 v191, v[152:155] offset:16384
	ds_write_b128 v202, v[148:151] offset:16384
	s_waitcnt lgkmcnt(11)
	v_mfma_f32_32x32x16_bf16 v[16:31], v[80:83], v[210:213], v[16:31]
	ds_read_b64_tr_b16 v[210:211], v190 offset:0x400
	ds_read_b64_tr_b16 v[212:213], v190 offset:0xc00
	v_mfma_f32_32x32x16_bf16 v[16:31], v[84:87], v[214:217], v[16:31]
	ds_read_b64_tr_b16 v[214:215], v190 offset:0x1400
	ds_read_b64_tr_b16 v[216:217], v190 offset:0x1c00
	v_mfma_f32_32x32x16_bf16 v[16:31], v[88:91], v[244:247], v[16:31]
	ds_read_b64_tr_b16 v[244:245], v190 offset:0x2400
	ds_read_b64_tr_b16 v[246:247], v190 offset:0x2c00
	v_mfma_f32_32x32x16_bf16 v[16:31], v[92:95], v[248:251], v[16:31]
	ds_read_b64_tr_b16 v[248:249], v190 offset:0x3400
	ds_read_b64_tr_b16 v[250:251], v190 offset:0x3c00
	s_waitcnt lgkmcnt(11)
	v_mfma_f32_32x32x16_bf16 v[32:47], v[80:83], v[2:5], v[32:47]
	ds_read_b64_tr_b16 v[2:3], v190 offset:0x600
	ds_read_b64_tr_b16 v[4:5], v190 offset:0xe00
	v_mfma_f32_32x32x16_bf16 v[32:47], v[84:87], v[6:9], v[32:47]
	ds_read_b64_tr_b16 v[6:7], v190 offset:0x1600
	ds_read_b64_tr_b16 v[8:9], v190 offset:0x1e00
	v_mfma_f32_32x32x16_bf16 v[32:47], v[88:91], v[10:13], v[32:47]
	ds_read_b64_tr_b16 v[10:11], v190 offset:0x2600
	ds_read_b64_tr_b16 v[12:13], v190 offset:0x2e00
	v_mfma_f32_32x32x16_bf16 v[32:47], v[92:95], v[162:165], v[32:47]
	ds_read_b64_tr_b16 v[162:163], v190 offset:0x3600
	ds_read_b64_tr_b16 v[164:165], v190 offset:0x3e00
	global_load_dwordx4 v[152:155], v198, s[100:101]
	global_load_dwordx4 v[148:151], v199, s[100:101]
	global_load_dwordx4 v[144:147], v0, s[100:101] offset:2048
	s_add_u32 s100, s100, 0x1a0000
	s_addc_u32 s101, s101, 0
	s_waitcnt lgkmcnt(8)
	v_mfma_f32_32x32x16_bf16 v[48:63], v[80:83], v[210:213], v[48:63]
	v_mfma_f32_32x32x16_bf16 v[48:63], v[84:87], v[214:217], v[48:63]
	v_mfma_f32_32x32x16_bf16 v[48:63], v[88:91], v[244:247], v[48:63]
	v_mfma_f32_32x32x16_bf16 v[48:63], v[92:95], v[248:251], v[48:63]
	s_waitcnt lgkmcnt(0)
	v_mfma_f32_32x32x16_bf16 v[64:79], v[80:83], v[2:5], v[64:79]
	v_mfma_f32_32x32x16_bf16 v[64:79], v[84:87], v[6:9], v[64:79]
	v_mfma_f32_32x32x16_bf16 v[64:79], v[88:91], v[10:13], v[64:79]
	v_mfma_f32_32x32x16_bf16 v[64:79], v[92:95], v[162:165], v[64:79]
	s_setprio 0
	s_barrier
	v_exp_f32_e32 v96, v96
	v_exp_f32_e32 v97, v97
	v_exp_f32_e32 v98, v98
	v_exp_f32_e32 v99, v99
	v_exp_f32_e32 v100, v100
	v_exp_f32_e32 v101, v101
	v_exp_f32_e32 v102, v102
	v_exp_f32_e32 v103, v103
	v_exp_f32_e32 v104, v104
	v_exp_f32_e32 v105, v105
	v_exp_f32_e32 v106, v106
	v_exp_f32_e32 v107, v107
	v_exp_f32_e32 v108, v108
	v_exp_f32_e32 v109, v109
	v_exp_f32_e32 v110, v110
	v_exp_f32_e32 v111, v111
	v_exp_f32_e32 v112, v112
	v_exp_f32_e32 v113, v113
	v_exp_f32_e32 v114, v114
	v_exp_f32_e32 v115, v115
	v_exp_f32_e32 v116, v116
	v_exp_f32_e32 v117, v117
	v_exp_f32_e32 v118, v118
	v_exp_f32_e32 v119, v119
	v_exp_f32_e32 v120, v120
	v_exp_f32_e32 v121, v121
	v_exp_f32_e32 v122, v122
	v_exp_f32_e32 v123, v123
	v_exp_f32_e32 v124, v124
	v_exp_f32_e32 v125, v125
	v_exp_f32_e32 v126, v126
	v_exp_f32_e32 v127, v127
	v_pk_add_f32 v[2:3], v[112:113], v[96:97]
	v_pk_add_f32 v[4:5], v[114:115], v[98:99]
	v_pk_add_f32 v[6:7], v[116:117], v[100:101]
	v_pk_add_f32 v[8:9], v[118:119], v[102:103]
	v_pk_add_f32 v[10:11], v[120:121], v[104:105]
	v_pk_add_f32 v[12:13], v[122:123], v[106:107]
	v_pk_add_f32 v[196:197], v[124:125], v[108:109]
	v_pk_add_f32 v[194:195], v[126:127], v[110:111]
	v_pk_add_f32 v[2:3], v[2:3], v[10:11]
	v_pk_add_f32 v[4:5], v[4:5], v[12:13]
	v_pk_add_f32 v[6:7], v[6:7], v[196:197]
	v_pk_add_f32 v[8:9], v[8:9], v[194:195]
	v_pk_add_f32 v[2:3], v[2:3], v[6:7]
	v_pk_add_f32 v[4:5], v[4:5], v[8:9]
	v_cvt_pk_bf16_f32 v80, v112, v113
	v_cvt_pk_bf16_f32 v81, v114, v115
	v_pk_add_f32 v[2:3], v[2:3], v[4:5]
	v_cvt_pk_bf16_f32 v82, v116, v117
	v_cvt_pk_bf16_f32 v83, v118, v119
	v_pk_add_f32 v[14:15], v[14:15], v[2:3]
	v_cvt_pk_bf16_f32 v84, v120, v121
	v_cvt_pk_bf16_f32 v85, v122, v123
	v_cvt_pk_bf16_f32 v86, v124, v125
	v_cvt_pk_bf16_f32 v87, v126, v127
	v_cvt_pk_bf16_f32 v88, v96, v97
	v_cvt_pk_bf16_f32 v89, v98, v99
	v_cvt_pk_bf16_f32 v90, v100, v101
	v_cvt_pk_bf16_f32 v91, v102, v103
	v_cvt_pk_bf16_f32 v92, v104, v105
	v_cvt_pk_bf16_f32 v93, v106, v107
	v_cvt_pk_bf16_f32 v94, v108, v109
	v_cvt_pk_bf16_f32 v95, v110, v111
	s_barrier
; #define A128_SBAR() __builtin_amdgcn_sched_barrier(0)
; #define A128_PK4(P, BASE, OUT) do { u32x4 w = {cvt_pk_bf16(P[BASE + 0], P[BASE + 1]), cvt_pk_bf16(P[BASE + 2], P[BASE + 3]), cvt_pk_bf16(P[BASE + 4], P[BASE + 5]), cvt_pk_bf16(P[BASE + 6], P[BASE + 7])}; \
;     OUT = __builtin_bit_cast(bf16x8, w); } while (0)
; #define A128_SWAIT() asm volatile("s_waitcnt vmcnt(3)" ::: "memory")
; __device__ __forceinline__ void finishSM(f32x16& p0, f32x16& p1, float alpha, float& l_reg, bf16x8& pa0, bf16x8& pa1, bf16x8& pa2, bf16x8& pa3) {
; #pragma unroll
;   for (int r = 0; r < 16; ++r) p1[r] = __builtin_amdgcn_exp2f(p1[r]);
;   typedef float f32x8_ __attribute__((ext_vector_type(8))); typedef float f32x2_ __attribute__((ext_vector_type(2)));
;   const f32x16 s16_ = p0 + p1; const f32x8_ s8_ = s16_.lo + s16_.hi; const f32x4 s4_ = s8_.lo + s8_.hi; const f32x2_ s2_ = s4_.lo + s4_.hi;
;   float ps = s2_.x + s2_.y;
;   { auto rr = __builtin_amdgcn_permlane32_swap(__float_as_uint(ps), __float_as_uint(ps), false, false); ps = __uint_as_float(rr[0]) + __uint_as_float(rr[1]); }
;   l_reg = l_reg * alpha + ps;
;     ...
;   A128_PK4(p0, 0, pa0); A128_PK4(p0, 8, pa1); A128_PK4(p1, 0, pa2); A128_PK4(p1, 8, pa3);
;     ...
; }
; __device__ __forceinline__ void unit(const bf16* __restrict__ Qb0, const bf16* __restrict__ Kh0, const bf16* __restrict__ Vh, bf16_t* Ob, int seq, char* lds, const int tid_in, const float lam, const float onem, const float* __restrict__ subw, const float* __restrict__ kmb  ) {
;     ...
;   for (int j = 1; j + 1 < NT; j += 2) {
;     A128_SBAR(); qkt(pB0, pB1, K_lds + SHM_K, qr, r32, hi);
;     finishSM(pA0, pA1, alA, l_reg, pa0, pa1, pa2, pa3); A128_SBAR();
;     A128_SLOAD(1, (j + 2) * KVBLK); A128_SBAR();
;     pv_d0(o, vb0, pa0, pa1, pa2, pa3); partialSM(pB0, pB1, m_reg, mnB, alB, nomax);
;     __syncthreads(); A128_SWAIT(); A128_SWRITE(0, 0);
;     if (!nomax) A128_RESC(alB); __syncthreads();
;     A128_SBAR(); qkt(pA0, pA1, K_lds, qr, r32, hi);
;     finishSM(pB0, pB1, alB, l_reg, pa0, pa1, pa2, pa3); A128_SBAR();
;     if (j + 3 < NT) A128_SLOAD(0, (j + 3) * KVBLK); A128_SBAR();
;     pv_d0(o, vb0 + (int)SHM_V, pa0, pa1, pa2, pa3); partialSM(pA0, pA1, m_reg, mnA, alA, nomax);
;     __syncthreads(); A128_SWAIT(); A128_SWRITE(1, 1);
;     if (!nomax) A128_RESC(alA); __syncthreads();
;   }
	s_setprio 1
	ds_read_b128 v[2:5], v204 offset:32768
	ds_read_b128 v[6:9], v204 offset:36864
	ds_read_b128 v[10:13], v205 offset:32768
	ds_read_b128 v[162:165], v205 offset:36864
	s_waitcnt lgkmcnt(2)
	v_mfma_f32_32x32x16_bf16 v[112:127], v[2:5], v[140:143], 0
	ds_read_b128 v[168:171], v192 offset:32768
	ds_read_b128 v[172:175], v192 offset:36864
	v_mfma_f32_32x32x16_bf16 v[96:111], v[6:9], v[140:143], 0
	ds_read_b128 v[176:179], v193 offset:32768
	ds_read_b128 v[194:197], v193 offset:36864
	s_waitcnt lgkmcnt(4)
	v_mfma_f32_32x32x16_bf16 v[112:127], v[10:13], v[136:139], v[112:127]
	ds_read_b64_tr_b16 v[210:211], v189 offset:0x0
	ds_read_b64_tr_b16 v[212:213], v189 offset:0x800
	ds_read_b64_tr_b16 v[214:215], v189 offset:0x1000
	v_mfma_f32_32x32x16_bf16 v[96:111], v[162:165], v[136:139], v[96:111]
	ds_read_b64_tr_b16 v[216:217], v189 offset:0x1800
	ds_read_b64_tr_b16 v[244:245], v189 offset:0x2000
	ds_read_b64_tr_b16 v[246:247], v189 offset:0x2800
	s_waitcnt lgkmcnt(8)
	v_mfma_f32_32x32x16_bf16 v[112:127], v[168:171], v[132:135], v[112:127]
	ds_read_b64_tr_b16 v[248:249], v189 offset:0x3000
	ds_read_b64_tr_b16 v[250:251], v189 offset:0x3800
	v_mfma_f32_32x32x16_bf16 v[96:111], v[172:175], v[132:135], v[96:111]
	ds_read_b64_tr_b16 v[2:3], v189 offset:0x200
	ds_read_b64_tr_b16 v[4:5], v189 offset:0xa00
	ds_read_b64_tr_b16 v[6:7], v189 offset:0x1200
	s_waitcnt lgkmcnt(11)
	v_mfma_f32_32x32x16_bf16 v[112:127], v[176:179], v[128:131], v[112:127]
	ds_read_b64_tr_b16 v[8:9], v189 offset:0x1a00
	ds_read_b64_tr_b16 v[10:11], v189 offset:0x2200
	ds_read_b64_tr_b16 v[12:13], v189 offset:0x2a00
	v_mfma_f32_32x32x16_bf16 v[96:111], v[194:197], v[128:131], v[96:111]
	ds_read_b64_tr_b16 v[162:163], v189 offset:0x3200
	ds_read_b64_tr_b16 v[164:165], v189 offset:0x3a00
	s_waitcnt vmcnt(3)
	ds_write_b128 v203, v[240:243] offset:40960
	ds_write_b128 v191, v[232:235]
	ds_write_b128 v202, v[236:239]
	s_waitcnt lgkmcnt(11)
	v_mfma_f32_32x32x16_bf16 v[16:31], v[80:83], v[210:213], v[16:31]
	ds_read_b64_tr_b16 v[210:211], v189 offset:0x400
	ds_read_b64_tr_b16 v[212:213], v189 offset:0xc00
	v_mfma_f32_32x32x16_bf16 v[16:31], v[84:87], v[214:217], v[16:31]
	ds_read_b64_tr_b16 v[214:215], v189 offset:0x1400
	ds_read_b64_tr_b16 v[216:217], v189 offset:0x1c00
	v_mfma_f32_32x32x16_bf16 v[16:31], v[88:91], v[244:247], v[16:31]
	ds_read_b64_tr_b16 v[244:245], v189 offset:0x2400
	ds_read_b64_tr_b16 v[246:247], v189 offset:0x2c00
	v_mfma_f32_32x32x16_bf16 v[16:31], v[92:95], v[248:251], v[16:31]
	ds_read_b64_tr_b16 v[248:249], v189 offset:0x3400
	ds_read_b64_tr_b16 v[250:251], v189 offset:0x3c00
	s_waitcnt lgkmcnt(11)
	v_mfma_f32_32x32x16_bf16 v[32:47], v[80:83], v[2:5], v[32:47]
	ds_read_b64_tr_b16 v[2:3], v189 offset:0x600
	ds_read_b64_tr_b16 v[4:5], v189 offset:0xe00
	v_mfma_f32_32x32x16_bf16 v[32:47], v[84:87], v[6:9], v[32:47]
	ds_read_b64_tr_b16 v[6:7], v189 offset:0x1600
	ds_read_b64_tr_b16 v[8:9], v189 offset:0x1e00
	v_mfma_f32_32x32x16_bf16 v[32:47], v[88:91], v[10:13], v[32:47]
	ds_read_b64_tr_b16 v[10:11], v189 offset:0x2600
	ds_read_b64_tr_b16 v[12:13], v189 offset:0x2e00
	v_mfma_f32_32x32x16_bf16 v[32:47], v[92:95], v[162:165], v[32:47]
	ds_read_b64_tr_b16 v[162:163], v189 offset:0x3600
	ds_read_b64_tr_b16 v[164:165], v189 offset:0x3e00
	global_load_dwordx4 v[232:235], v198, s[100:101]
	global_load_dwordx4 v[236:239], v199, s[100:101]
	global_load_dwordx4 v[240:243], v0, s[100:101] offset:2048
	s_add_u32 s100, s100, 0x1a0000
	s_addc_u32 s101, s101, 0
	s_waitcnt lgkmcnt(8)
	v_mfma_f32_32x32x16_bf16 v[48:63], v[80:83], v[210:213], v[48:63]
	v_mfma_f32_32x32x16_bf16 v[48:63], v[84:87], v[214:217], v[48:63]
	v_mfma_f32_32x32x16_bf16 v[48:63], v[88:91], v[244:247], v[48:63]
	v_mfma_f32_32x32x16_bf16 v[48:63], v[92:95], v[248:251], v[48:63]
	s_waitcnt lgkmcnt(0)
	v_mfma_f32_32x32x16_bf16 v[64:79], v[80:83], v[2:5], v[64:79]
	v_mfma_f32_32x32x16_bf16 v[64:79], v[84:87], v[6:9], v[64:79]
	v_mfma_f32_32x32x16_bf16 v[64:79], v[88:91], v[10:13], v[64:79]
	v_mfma_f32_32x32x16_bf16 v[64:79], v[92:95], v[162:165], v[64:79]
	s_setprio 0
	s_barrier
	s_cmp_ge_u32 s38, s27
	s_cbranch_scc1 .Lfa_exit
	s_add_i32 s38, s38, 2
	v_exp_f32_e32 v96, v96
	v_exp_f32_e32 v97, v97
	v_exp_f32_e32 v98, v98
	v_exp_f32_e32 v99, v99
	v_exp_f32_e32 v100, v100
	v_exp_f32_e32 v101, v101
	v_exp_f32_e32 v102, v102
	v_exp_f32_e32 v103, v103
	v_exp_f32_e32 v104, v104
	v_exp_f32_e32 v105, v105
	v_exp_f32_e32 v106, v106
	v_exp_f32_e32 v107, v107
	v_exp_f32_e32 v108, v108
	v_exp_f32_e32 v109, v109
	v_exp_f32_e32 v110, v110
	v_exp_f32_e32 v111, v111
	v_exp_f32_e32 v112, v112
	v_exp_f32_e32 v113, v113
	v_exp_f32_e32 v114, v114
	v_exp_f32_e32 v115, v115
	v_exp_f32_e32 v116, v116
	v_exp_f32_e32 v117, v117
	v_exp_f32_e32 v118, v118
	v_exp_f32_e32 v119, v119
	v_exp_f32_e32 v120, v120
	v_exp_f32_e32 v121, v121
	v_exp_f32_e32 v122, v122
	v_exp_f32_e32 v123, v123
	v_exp_f32_e32 v124, v124
	v_exp_f32_e32 v125, v125
	v_exp_f32_e32 v126, v126
	v_exp_f32_e32 v127, v127
	v_pk_add_f32 v[2:3], v[112:113], v[96:97]
	v_pk_add_f32 v[4:5], v[114:115], v[98:99]
	v_pk_add_f32 v[6:7], v[116:117], v[100:101]
	v_pk_add_f32 v[8:9], v[118:119], v[102:103]
	v_pk_add_f32 v[10:11], v[120:121], v[104:105]
	v_pk_add_f32 v[12:13], v[122:123], v[106:107]
	v_pk_add_f32 v[196:197], v[124:125], v[108:109]
	v_pk_add_f32 v[194:195], v[126:127], v[110:111]
	v_pk_add_f32 v[2:3], v[2:3], v[10:11]
	v_pk_add_f32 v[4:5], v[4:5], v[12:13]
	v_pk_add_f32 v[6:7], v[6:7], v[196:197]
	v_pk_add_f32 v[8:9], v[8:9], v[194:195]
	v_pk_add_f32 v[2:3], v[2:3], v[6:7]
	v_pk_add_f32 v[4:5], v[4:5], v[8:9]
	v_cvt_pk_bf16_f32 v80, v112, v113
	v_cvt_pk_bf16_f32 v81, v114, v115
	v_pk_add_f32 v[2:3], v[2:3], v[4:5]
	v_cvt_pk_bf16_f32 v82, v116, v117
	v_cvt_pk_bf16_f32 v83, v118, v119
	v_pk_add_f32 v[14:15], v[14:15], v[2:3]
	v_cvt_pk_bf16_f32 v84, v120, v121
	v_cvt_pk_bf16_f32 v85, v122, v123
	v_cvt_pk_bf16_f32 v86, v124, v125
	v_cvt_pk_bf16_f32 v87, v126, v127
	v_cvt_pk_bf16_f32 v88, v96, v97
	v_cvt_pk_bf16_f32 v89, v98, v99
	v_cvt_pk_bf16_f32 v90, v100, v101
	v_cvt_pk_bf16_f32 v91, v102, v103
	v_cvt_pk_bf16_f32 v92, v104, v105
	v_cvt_pk_bf16_f32 v93, v106, v107
	v_cvt_pk_bf16_f32 v94, v108, v109
	v_cvt_pk_bf16_f32 v95, v110, v111
	s_branch .Lfa_loop
